# v71 with 9 (instead of 5) row-steps of the phase-5 epilogue loads hoisted
# speedup vs baseline: 1.0164x; 1.0016x over previous
.LBB0_332:
	ds_read_b128 v[142:145], v163
	ds_read_b128 v[146:149], v163 offset:1024
	ds_read_b128 v[166:169], v163 offset:2048
	ds_read_b128 v[170:173], v163 offset:3072
	s_add_u32 s34, s30, 0xfffc0080
	s_addc_u32 s35, s31, -1
	s_cmp_eq_u32 s63, 12
	s_cselect_b32 s37, s27, s35
	s_cselect_b32 s36, s26, s34
	s_cselect_b32 s35, s29, s62
	s_cselect_b32 s34, s28, s61
	v_lshl_add_u64 v[206:207], s[30:31], 0, v[136:137]
	s_add_i32 m0, s43, 0xc000
	ds_read_b128 v[174:177], v164
	ds_read_b128 v[178:181], v164 offset:1024
	ds_read_b128 v[182:185], v164 offset:2048
	ds_read_b128 v[186:189], v164 offset:3072
	ds_read_b128 v[190:193], v164 offset:4096
	ds_read_b128 v[194:197], v164 offset:5120
	ds_read_b128 v[198:201], v164 offset:6144
	ds_read_b128 v[202:205], v164 offset:7168
	global_load_lds_dwordx4 v[206:207], off
	v_lshl_add_u64 v[206:207], s[30:31], 0, v[138:139]
	s_add_i32 m0, s43, 0xe000
	s_nop 0
	global_load_lds_dwordx4 v[206:207], off
	s_waitcnt lgkmcnt(8)
	s_barrier
	s_waitcnt lgkmcnt(0)
	s_setprio 1
	s_waitcnt lgkmcnt(0)
	v_mfma_f32_16x16x32_bf16 v[124:127], v[142:145], v[174:177], v[124:127]
	v_mfma_f32_16x16x32_bf16 v[120:123], v[166:169], v[174:177], v[120:123]
	v_mfma_f32_16x16x32_bf16 v[112:115], v[142:145], v[182:185], v[112:115]
	v_mfma_f32_16x16x32_bf16 v[104:107], v[166:169], v[182:185], v[104:107]
	v_mfma_f32_16x16x32_bf16 v[96:99], v[142:145], v[190:193], v[96:99]
	v_mfma_f32_16x16x32_bf16 v[88:91], v[166:169], v[190:193], v[88:91]
	v_mfma_f32_16x16x32_bf16 v[80:83], v[142:145], v[198:201], v[80:83]
	v_mfma_f32_16x16x32_bf16 v[72:75], v[166:169], v[198:201], v[72:75]
	v_mfma_f32_16x16x32_bf16 v[124:127], v[146:149], v[178:181], v[124:127]
	v_mfma_f32_16x16x32_bf16 v[120:123], v[170:173], v[178:181], v[120:123]
	v_mfma_f32_16x16x32_bf16 v[112:115], v[146:149], v[186:189], v[112:115]
	v_mfma_f32_16x16x32_bf16 v[104:107], v[170:173], v[186:189], v[104:107]
	v_mfma_f32_16x16x32_bf16 v[96:99], v[146:149], v[194:197], v[96:99]
	v_mfma_f32_16x16x32_bf16 v[88:91], v[170:173], v[194:197], v[88:91]
	v_mfma_f32_16x16x32_bf16 v[80:83], v[146:149], v[202:205], v[80:83]
	v_mfma_f32_16x16x32_bf16 v[72:75], v[170:173], v[202:205], v[72:75]
	s_setprio 0
	s_barrier
	s_add_i32 s64, s57, s42
	v_lshl_add_u64 v[222:223], s[34:35], 0, v[130:131]
	s_mov_b32 m0, s64
	ds_read_b128 v[206:209], v165
	ds_read_b128 v[210:213], v165 offset:1024
	ds_read_b128 v[214:217], v165 offset:2048
	ds_read_b128 v[218:221], v165 offset:3072
	global_load_lds_dwordx4 v[222:223], off
	v_lshl_add_u64 v[224:225], s[34:35], 0, v[134:135]
	s_add_i32 m0, s64, 0x2000
	s_nop 0
	global_load_lds_dwordx4 v[224:225], off
	s_barrier
	s_waitcnt lgkmcnt(0)
	s_setprio 1
	s_waitcnt lgkmcnt(0)
	v_mfma_f32_16x16x32_bf16 v[116:119], v[206:209], v[174:177], v[116:119]
	v_mfma_f32_16x16x32_bf16 v[108:111], v[214:217], v[174:177], v[108:111]
	v_mfma_f32_16x16x32_bf16 v[100:103], v[206:209], v[182:185], v[100:103]
	v_mfma_f32_16x16x32_bf16 v[92:95], v[214:217], v[182:185], v[92:95]
	v_mfma_f32_16x16x32_bf16 v[84:87], v[206:209], v[190:193], v[84:87]
	v_mfma_f32_16x16x32_bf16 v[76:79], v[214:217], v[190:193], v[76:79]
	v_mfma_f32_16x16x32_bf16 v[68:71], v[206:209], v[198:201], v[68:71]
	v_mfma_f32_16x16x32_bf16 v[64:67], v[214:217], v[198:201], v[64:67]
	v_mfma_f32_16x16x32_bf16 v[116:119], v[210:213], v[178:181], v[116:119]
	v_mfma_f32_16x16x32_bf16 v[108:111], v[218:221], v[178:181], v[108:111]
	v_mfma_f32_16x16x32_bf16 v[100:103], v[210:213], v[186:189], v[100:103]
	v_mfma_f32_16x16x32_bf16 v[92:95], v[218:221], v[186:189], v[92:95]
	v_mfma_f32_16x16x32_bf16 v[84:87], v[210:213], v[194:197], v[84:87]
	v_mfma_f32_16x16x32_bf16 v[76:79], v[218:221], v[194:197], v[76:79]
	v_mfma_f32_16x16x32_bf16 v[68:71], v[210:213], v[202:205], v[68:71]
	v_mfma_f32_16x16x32_bf16 v[64:67], v[218:221], v[202:205], v[64:67]
	s_setprio 0
	s_mov_b32 m0, s43
	v_lshl_add_u64 v[226:227], s[36:37], 0, v[128:129]
	s_barrier
	ds_read_b128 v[174:177], v164 offset:16384
	ds_read_b128 v[178:181], v164 offset:17408
	ds_read_b128 v[182:185], v164 offset:18432
	ds_read_b128 v[186:189], v164 offset:19456
	ds_read_b128 v[190:193], v164 offset:20480
	ds_read_b128 v[194:197], v164 offset:21504
	ds_read_b128 v[198:201], v164 offset:22528
	ds_read_b128 v[202:205], v164 offset:23552
	global_load_lds_dwordx4 v[226:227], off
	v_lshl_add_u64 v[228:229], s[36:37], 0, v[132:133]
	s_mov_b32 m0, s44
	s_nop 0
	global_load_lds_dwordx4 v[228:229], off
	s_barrier
	s_waitcnt lgkmcnt(0)
	s_setprio 1
	s_waitcnt lgkmcnt(0)
	v_mfma_f32_16x16x32_bf16 v[60:63], v[142:145], v[174:177], v[60:63]
	v_mfma_f32_16x16x32_bf16 v[56:59], v[166:169], v[174:177], v[56:59]
	v_mfma_f32_16x16x32_bf16 v[48:51], v[142:145], v[182:185], v[48:51]
	v_mfma_f32_16x16x32_bf16 v[40:43], v[166:169], v[182:185], v[40:43]
	v_mfma_f32_16x16x32_bf16 v[32:35], v[142:145], v[190:193], v[32:35]
	v_mfma_f32_16x16x32_bf16 v[24:27], v[166:169], v[190:193], v[24:27]
	v_mfma_f32_16x16x32_bf16 v[12:15], v[142:145], v[198:201], v[12:15]
	v_mfma_f32_16x16x32_bf16 v[8:11], v[166:169], v[198:201], v[8:11]
	v_mfma_f32_16x16x32_bf16 v[60:63], v[146:149], v[178:181], v[60:63]
	v_mfma_f32_16x16x32_bf16 v[56:59], v[170:173], v[178:181], v[56:59]
	v_mfma_f32_16x16x32_bf16 v[48:51], v[146:149], v[186:189], v[48:51]
	v_mfma_f32_16x16x32_bf16 v[40:43], v[170:173], v[186:189], v[40:43]
	v_mfma_f32_16x16x32_bf16 v[32:35], v[146:149], v[194:197], v[32:35]
	v_mfma_f32_16x16x32_bf16 v[24:27], v[170:173], v[194:197], v[24:27]
	v_mfma_f32_16x16x32_bf16 v[12:15], v[146:149], v[202:205], v[12:15]
	v_mfma_f32_16x16x32_bf16 v[8:11], v[170:173], v[202:205], v[8:11]
	s_setprio 0
	s_barrier
	s_add_u32 s64, s34, 0x40000
	s_addc_u32 s65, s35, 0
	s_add_i32 s66, s58, s42
	v_lshl_add_u64 v[142:143], s[64:65], 0, v[130:131]
	s_mov_b32 m0, s66
	s_nop 0
	global_load_lds_dwordx4 v[142:143], off
	v_lshl_add_u64 v[142:143], s[64:65], 0, v[134:135]
	s_add_i32 m0, s66, 0x2000
	s_nop 0
	global_load_lds_dwordx4 v[142:143], off
	s_waitcnt vmcnt(6)
	s_barrier
	s_setprio 1
	v_mfma_f32_16x16x32_bf16 v[52:55], v[206:209], v[174:177], v[52:55]
	v_mfma_f32_16x16x32_bf16 v[44:47], v[214:217], v[174:177], v[44:47]
	v_mfma_f32_16x16x32_bf16 v[36:39], v[206:209], v[182:185], v[36:39]
	v_mfma_f32_16x16x32_bf16 v[28:31], v[214:217], v[182:185], v[28:31]
	v_mfma_f32_16x16x32_bf16 v[20:23], v[206:209], v[190:193], v[20:23]
	v_mfma_f32_16x16x32_bf16 v[16:19], v[214:217], v[190:193], v[16:19]
	v_mfma_f32_16x16x32_bf16 v[4:7], v[206:209], v[198:201], v[4:7]
	v_mfma_f32_16x16x32_bf16 v[0:3], v[214:217], v[198:201], v[0:3]
	v_mfma_f32_16x16x32_bf16 v[52:55], v[210:213], v[178:181], v[52:55]
	v_mfma_f32_16x16x32_bf16 v[44:47], v[218:221], v[178:181], v[44:47]
	v_mfma_f32_16x16x32_bf16 v[36:39], v[210:213], v[186:189], v[36:39]
	v_mfma_f32_16x16x32_bf16 v[28:31], v[218:221], v[186:189], v[28:31]
	v_mfma_f32_16x16x32_bf16 v[20:23], v[210:213], v[194:197], v[20:23]
	v_mfma_f32_16x16x32_bf16 v[16:19], v[218:221], v[194:197], v[16:19]
	v_mfma_f32_16x16x32_bf16 v[4:7], v[210:213], v[202:205], v[4:7]
	v_mfma_f32_16x16x32_bf16 v[0:3], v[218:221], v[202:205], v[0:3]
	s_setprio 0
	s_add_i32 s64, 0, 0x18000
	v_add_u32_e32 v170, s64, v151
	s_barrier
	ds_read_b128 v[142:145], v170
	ds_read_b128 v[146:149], v170 offset:1024
	ds_read_b128 v[166:169], v170 offset:2048
	ds_read_b128 v[170:173], v170 offset:3072
	s_add_u32 s36, s36, 0x40000
	s_addc_u32 s37, s37, 0
	s_mov_b32 m0, s45
	v_lshl_add_u64 v[206:207], s[36:37], 0, v[128:129]
	ds_read_b128 v[174:177], v164 offset:32768
	ds_read_b128 v[178:181], v164 offset:33792
	ds_read_b128 v[182:185], v164 offset:34816
	ds_read_b128 v[186:189], v164 offset:35840
	ds_read_b128 v[190:193], v164 offset:36864
	ds_read_b128 v[194:197], v164 offset:37888
	ds_read_b128 v[198:201], v164 offset:38912
	ds_read_b128 v[202:205], v164 offset:39936
	global_load_lds_dwordx4 v[206:207], off
	v_lshl_add_u64 v[206:207], s[36:37], 0, v[132:133]
	s_mov_b32 m0, s46
	s_nop 0
	global_load_lds_dwordx4 v[206:207], off
	s_waitcnt lgkmcnt(8)
	s_barrier
	s_waitcnt lgkmcnt(0)
	s_setprio 1
	s_waitcnt lgkmcnt(0)
	v_mfma_f32_16x16x32_bf16 v[124:127], v[142:145], v[174:177], v[124:127]
	v_mfma_f32_16x16x32_bf16 v[120:123], v[166:169], v[174:177], v[120:123]
	v_mfma_f32_16x16x32_bf16 v[112:115], v[142:145], v[182:185], v[112:115]
	v_mfma_f32_16x16x32_bf16 v[104:107], v[166:169], v[182:185], v[104:107]
	v_mfma_f32_16x16x32_bf16 v[96:99], v[142:145], v[190:193], v[96:99]
	v_mfma_f32_16x16x32_bf16 v[88:91], v[166:169], v[190:193], v[88:91]
	v_mfma_f32_16x16x32_bf16 v[80:83], v[142:145], v[198:201], v[80:83]
	v_mfma_f32_16x16x32_bf16 v[72:75], v[166:169], v[198:201], v[72:75]
	v_mfma_f32_16x16x32_bf16 v[124:127], v[146:149], v[178:181], v[124:127]
	v_mfma_f32_16x16x32_bf16 v[120:123], v[170:173], v[178:181], v[120:123]
	v_mfma_f32_16x16x32_bf16 v[112:115], v[146:149], v[186:189], v[112:115]
	v_mfma_f32_16x16x32_bf16 v[104:107], v[170:173], v[186:189], v[104:107]
	v_mfma_f32_16x16x32_bf16 v[96:99], v[146:149], v[194:197], v[96:99]
	v_mfma_f32_16x16x32_bf16 v[88:91], v[170:173], v[194:197], v[88:91]
	v_mfma_f32_16x16x32_bf16 v[80:83], v[146:149], v[202:205], v[80:83]
	v_mfma_f32_16x16x32_bf16 v[72:75], v[170:173], v[202:205], v[72:75]
	s_setprio 0
	s_barrier
	s_add_i32 s36, 0, 0x1c000
	s_add_i32 s37, s64, s42
	v_add_u32_e32 v218, s36, v151
	v_lshl_add_u64 v[222:223], v[222:223], 0, s[10:11]
	s_mov_b32 m0, s37
	ds_read_b128 v[206:209], v218
	ds_read_b128 v[210:213], v218 offset:1024
	ds_read_b128 v[214:217], v218 offset:2048
	ds_read_b128 v[218:221], v218 offset:3072
	global_load_lds_dwordx4 v[222:223], off
	v_lshl_add_u64 v[222:223], v[224:225], 0, s[10:11]
	s_add_i32 m0, s37, 0x2000
	s_nop 0
	global_load_lds_dwordx4 v[222:223], off
	s_barrier
	s_waitcnt lgkmcnt(0)
	s_setprio 1
	s_waitcnt lgkmcnt(0)
	v_mfma_f32_16x16x32_bf16 v[116:119], v[206:209], v[174:177], v[116:119]
	v_mfma_f32_16x16x32_bf16 v[108:111], v[214:217], v[174:177], v[108:111]
	v_mfma_f32_16x16x32_bf16 v[100:103], v[206:209], v[182:185], v[100:103]
	v_mfma_f32_16x16x32_bf16 v[92:95], v[214:217], v[182:185], v[92:95]
	v_mfma_f32_16x16x32_bf16 v[84:87], v[206:209], v[190:193], v[84:87]
	v_mfma_f32_16x16x32_bf16 v[76:79], v[214:217], v[190:193], v[76:79]
	v_mfma_f32_16x16x32_bf16 v[68:71], v[206:209], v[198:201], v[68:71]
	v_mfma_f32_16x16x32_bf16 v[64:67], v[214:217], v[198:201], v[64:67]
	v_mfma_f32_16x16x32_bf16 v[116:119], v[210:213], v[178:181], v[116:119]
	v_mfma_f32_16x16x32_bf16 v[108:111], v[218:221], v[178:181], v[108:111]
	v_mfma_f32_16x16x32_bf16 v[100:103], v[210:213], v[186:189], v[100:103]
	v_mfma_f32_16x16x32_bf16 v[92:95], v[218:221], v[186:189], v[92:95]
	v_mfma_f32_16x16x32_bf16 v[84:87], v[210:213], v[194:197], v[84:87]
	v_mfma_f32_16x16x32_bf16 v[76:79], v[218:221], v[194:197], v[76:79]
	v_mfma_f32_16x16x32_bf16 v[68:71], v[210:213], v[202:205], v[68:71]
	v_mfma_f32_16x16x32_bf16 v[64:67], v[218:221], v[202:205], v[64:67]
	s_setprio 0
	s_mov_b32 m0, s51
	v_lshl_add_u64 v[222:223], v[226:227], 0, s[10:11]
	s_barrier
	ds_read_b128 v[174:177], v164 offset:49152
	ds_read_b128 v[178:181], v164 offset:50176
	ds_read_b128 v[182:185], v164 offset:51200
	ds_read_b128 v[186:189], v164 offset:52224
	ds_read_b128 v[190:193], v164 offset:53248
	ds_read_b128 v[194:197], v164 offset:54272
	ds_read_b128 v[198:201], v164 offset:55296
	ds_read_b128 v[202:205], v164 offset:56320
	global_load_lds_dwordx4 v[222:223], off
	v_lshl_add_u64 v[222:223], v[228:229], 0, s[10:11]
	s_mov_b32 m0, s52
	s_nop 0
	global_load_lds_dwordx4 v[222:223], off
	s_barrier
	s_waitcnt lgkmcnt(0)
	s_setprio 1
	s_waitcnt lgkmcnt(0)
	v_mfma_f32_16x16x32_bf16 v[60:63], v[142:145], v[174:177], v[60:63]
	v_mfma_f32_16x16x32_bf16 v[56:59], v[166:169], v[174:177], v[56:59]
	v_mfma_f32_16x16x32_bf16 v[48:51], v[142:145], v[182:185], v[48:51]
	v_mfma_f32_16x16x32_bf16 v[40:43], v[166:169], v[182:185], v[40:43]
	v_mfma_f32_16x16x32_bf16 v[32:35], v[142:145], v[190:193], v[32:35]
	v_mfma_f32_16x16x32_bf16 v[24:27], v[166:169], v[190:193], v[24:27]
	v_mfma_f32_16x16x32_bf16 v[12:15], v[142:145], v[198:201], v[12:15]
	v_mfma_f32_16x16x32_bf16 v[8:11], v[166:169], v[198:201], v[8:11]
	v_mfma_f32_16x16x32_bf16 v[60:63], v[146:149], v[178:181], v[60:63]
	v_mfma_f32_16x16x32_bf16 v[56:59], v[170:173], v[178:181], v[56:59]
	v_mfma_f32_16x16x32_bf16 v[48:51], v[146:149], v[186:189], v[48:51]
	v_mfma_f32_16x16x32_bf16 v[40:43], v[170:173], v[186:189], v[40:43]
	v_mfma_f32_16x16x32_bf16 v[32:35], v[146:149], v[194:197], v[32:35]
	v_mfma_f32_16x16x32_bf16 v[24:27], v[170:173], v[194:197], v[24:27]
	v_mfma_f32_16x16x32_bf16 v[12:15], v[146:149], v[202:205], v[12:15]
	v_mfma_f32_16x16x32_bf16 v[8:11], v[170:173], v[202:205], v[8:11]
	s_setprio 0
	s_barrier
	s_add_u32 s34, s34, 0x40080
	s_addc_u32 s35, s35, 0
	s_add_i32 s36, s36, s42
	v_lshl_add_u64 v[142:143], s[34:35], 0, v[130:131]
	s_mov_b32 m0, s36
	s_nop 0
	global_load_lds_dwordx4 v[142:143], off
	v_lshl_add_u64 v[142:143], s[34:35], 0, v[134:135]
	s_add_i32 m0, s36, 0x2000
	s_nop 0
	global_load_lds_dwordx4 v[142:143], off
	s_waitcnt vmcnt(6)
	s_barrier
	s_setprio 1
	v_mfma_f32_16x16x32_bf16 v[52:55], v[206:209], v[174:177], v[52:55]
	v_mfma_f32_16x16x32_bf16 v[44:47], v[214:217], v[174:177], v[44:47]
	v_mfma_f32_16x16x32_bf16 v[36:39], v[206:209], v[182:185], v[36:39]
	v_mfma_f32_16x16x32_bf16 v[28:31], v[214:217], v[182:185], v[28:31]
	v_mfma_f32_16x16x32_bf16 v[20:23], v[206:209], v[190:193], v[20:23]
	v_mfma_f32_16x16x32_bf16 v[16:19], v[214:217], v[190:193], v[16:19]
	v_mfma_f32_16x16x32_bf16 v[4:7], v[206:209], v[198:201], v[4:7]
	v_mfma_f32_16x16x32_bf16 v[0:3], v[214:217], v[198:201], v[0:3]
	v_mfma_f32_16x16x32_bf16 v[52:55], v[210:213], v[178:181], v[52:55]
	v_mfma_f32_16x16x32_bf16 v[44:47], v[218:221], v[178:181], v[44:47]
	v_mfma_f32_16x16x32_bf16 v[36:39], v[210:213], v[186:189], v[36:39]
	v_mfma_f32_16x16x32_bf16 v[28:31], v[218:221], v[186:189], v[28:31]
	v_mfma_f32_16x16x32_bf16 v[20:23], v[210:213], v[194:197], v[20:23]
	v_mfma_f32_16x16x32_bf16 v[16:19], v[218:221], v[194:197], v[16:19]
	v_mfma_f32_16x16x32_bf16 v[4:7], v[210:213], v[202:205], v[4:7]
	v_mfma_f32_16x16x32_bf16 v[0:3], v[218:221], v[202:205], v[0:3]
	s_setprio 0
	s_add_i32 s63, s63, 2
	s_add_u32 s30, s30, 0x100
	s_addc_u32 s31, s31, 0
	s_add_u32 s61, s61, 0x100
	s_addc_u32 s62, s62, 0
	s_cmp_gt_u32 s63, 13
	s_barrier
	s_cbranch_scc0 .LBB0_332
	v_add_u32_e32 v142, s60, v150
	s_cmp_lt_i32 s60, 0x8000
	v_readlane_b32 s60, v254, 0
	v_add_u32_e32 v144, s50, v152
	v_readlane_b32 s61, v254, 1
	v_ashrrev_i32_e32 v143, 31, v142
	s_mov_b64 s[36:37], s[60:61]
	v_ashrrev_i32_e32 v145, 31, v144
	v_lshlrev_b64 v[146:147], 10, v[142:143]
	s_cselect_b32 s31, s37, s56
	s_cselect_b32 s30, s36, s55
	v_lshl_add_u64 v[144:145], v[146:147], 0, v[144:145]
	v_lshl_add_u64 v[170:171], v[144:145], 2, s[30:31]
	global_load_dwordx4 v[146:149], v[170:171], off
	global_load_dwordx4 v[166:169], v[170:171], off offset:16
	global_load_dwordx4 v[178:181], v[170:171], off offset:512
	global_load_dwordx4 v[182:185], v[170:171], off offset:528
	v_lshl_add_u64 v[250:251], v[144:145], 0, s[12:13]
	v_lshl_add_u64 v[252:253], v[250:251], 2, s[30:31]
	global_load_dwordx4 v[186:189], v[252:253], off
	v_lshl_add_u64 v[250:251], v[144:145], 0, s[12:13]
	v_lshl_add_u64 v[252:253], v[250:251], 2, s[30:31]
	global_load_dwordx4 v[190:193], v[252:253], off offset:16
	v_lshl_add_u64 v[250:251], v[144:145], 0, s[12:13]
	v_lshl_add_u64 v[252:253], v[250:251], 2, s[30:31]
	global_load_dwordx4 v[194:197], v[252:253], off offset:512
	v_lshl_add_u64 v[250:251], v[144:145], 0, s[12:13]
	v_lshl_add_u64 v[252:253], v[250:251], 2, s[30:31]
	global_load_dwordx4 v[198:201], v[252:253], off offset:528
	v_lshl_add_u64 v[250:251], v[144:145], 0, s[14:15]
	v_lshl_add_u64 v[252:253], v[250:251], 2, s[30:31]
	global_load_dwordx4 v[202:205], v[252:253], off
	v_lshl_add_u64 v[250:251], v[144:145], 0, s[14:15]
	v_lshl_add_u64 v[252:253], v[250:251], 2, s[30:31]
	global_load_dwordx4 v[206:209], v[252:253], off offset:16
	v_lshl_add_u64 v[250:251], v[144:145], 0, s[14:15]
	v_lshl_add_u64 v[252:253], v[250:251], 2, s[30:31]
	global_load_dwordx4 v[210:213], v[252:253], off offset:512
	v_lshl_add_u64 v[250:251], v[144:145], 0, s[14:15]
	v_lshl_add_u64 v[252:253], v[250:251], 2, s[30:31]
	global_load_dwordx4 v[214:217], v[252:253], off offset:528
	v_lshl_add_u64 v[250:251], v[144:145], 0, s[16:17]
	v_lshl_add_u64 v[252:253], v[250:251], 2, s[30:31]
	global_load_dwordx4 v[218:221], v[252:253], off
	v_lshl_add_u64 v[250:251], v[144:145], 0, s[16:17]
	v_lshl_add_u64 v[252:253], v[250:251], 2, s[30:31]
	global_load_dwordx4 v[222:225], v[252:253], off offset:16
	v_lshl_add_u64 v[250:251], v[144:145], 0, s[16:17]
	v_lshl_add_u64 v[252:253], v[250:251], 2, s[30:31]
	global_load_dwordx4 v[226:229], v[252:253], off offset:512
	v_lshl_add_u64 v[250:251], v[144:145], 0, s[16:17]
	v_lshl_add_u64 v[252:253], v[250:251], 2, s[30:31]
	global_load_dwordx4 v[230:233], v[252:253], off offset:528
	v_lshl_add_u64 v[250:251], v[144:145], 0, s[18:19]
	v_lshl_add_u64 v[252:253], v[250:251], 2, s[30:31]
	global_load_dwordx4 v[234:237], v[252:253], off
	v_lshl_add_u64 v[250:251], v[144:145], 0, s[18:19]
	v_lshl_add_u64 v[252:253], v[250:251], 2, s[30:31]
	global_load_dwordx4 v[238:241], v[252:253], off offset:16
	v_lshl_add_u64 v[250:251], v[144:145], 0, s[18:19]
	v_lshl_add_u64 v[252:253], v[250:251], 2, s[30:31]
	global_load_dwordx4 v[242:245], v[252:253], off offset:512
	v_lshl_add_u64 v[250:251], v[144:145], 0, s[18:19]
	v_lshl_add_u64 v[252:253], v[250:251], 2, s[30:31]
	global_load_dwordx4 v[246:249], v[252:253], off offset:528
	v_readlane_b32 s34, v254, 56
	v_readlane_b32 s35, v254, 57
	v_lshl_add_u64 v[174:175], v[144:145], 0, s[12:13]
	v_lshl_add_u64 v[176:177], v[174:175], 2, s[30:31]
	v_lshl_add_u64 v[172:173], v[144:145], 1, s[34:35]
	v_lshl_add_u64 v[174:175], v[174:175], 1, s[34:35]
	v_readlane_b32 s62, v254, 2
	v_readlane_b32 s63, v254, 3
	v_readlane_b32 s64, v254, 4
	v_readlane_b32 s65, v254, 5
	v_readlane_b32 s66, v254, 6
	v_readlane_b32 s67, v254, 7
	v_readlane_b32 s68, v254, 8
	v_readlane_b32 s69, v254, 9
	v_readlane_b32 s70, v254, 10
	v_readlane_b32 s71, v254, 11
	v_readlane_b32 s72, v254, 12
	v_readlane_b32 s73, v254, 13
	v_readlane_b32 s74, v254, 14
	v_readlane_b32 s75, v254, 15
	s_waitcnt vmcnt(18)
	v_pk_add_f32 v[126:127], v[126:127], v[148:149]
	v_pk_add_f32 v[124:125], v[124:125], v[146:147]
	v_pk_add_f32 v[122:123], v[122:123], v[168:169]
	v_pk_add_f32 v[120:121], v[120:121], v[166:167]
	v_cvt_pk_bf16_f32 v146, v124, v125
	v_cvt_pk_bf16_f32 v147, v126, v127
	v_cvt_pk_bf16_f32 v149, v122, v123
	s_nop 0
	v_cvt_pk_bf16_f32 v148, v120, v121
	global_store_dwordx4 v[172:173], v[146:149], off
	s_nop 0
	s_waitcnt vmcnt(17)
	s_nop 1
	v_mov_b32_e32 v146, v178
	v_mov_b32_e32 v147, v179
	v_mov_b32_e32 v148, v180
	v_mov_b32_e32 v149, v181
	v_mov_b32_e32 v166, v182
	v_mov_b32_e32 v167, v183
	v_mov_b32_e32 v168, v184
	v_mov_b32_e32 v169, v185
	v_pk_add_f32 v[118:119], v[118:119], v[148:149]
	v_pk_add_f32 v[148:149], v[116:117], v[146:147]
	v_pk_add_f32 v[116:117], v[110:111], v[168:169]
	v_pk_add_f32 v[146:147], v[108:109], v[166:167]
	v_cvt_pk_bf16_f32 v108, v148, v149
	v_cvt_pk_bf16_f32 v109, v118, v119
	v_cvt_pk_bf16_f32 v111, v116, v117
	s_nop 0
	v_cvt_pk_bf16_f32 v110, v146, v147
	global_store_dwordx4 v[172:173], v[108:111], off offset:256
	s_nop 0
	s_waitcnt vmcnt(16)
	s_nop 1
	v_mov_b32_e32 v166, v186
	v_mov_b32_e32 v167, v187
	v_mov_b32_e32 v168, v188
	v_mov_b32_e32 v169, v189
	v_mov_b32_e32 v170, v190
	v_mov_b32_e32 v171, v191
	v_mov_b32_e32 v172, v192
	v_mov_b32_e32 v173, v193
	v_pk_add_f32 v[108:109], v[114:115], v[168:169]
	v_pk_add_f32 v[110:111], v[112:113], v[166:167]
	v_pk_add_f32 v[106:107], v[106:107], v[172:173]
	v_pk_add_f32 v[104:105], v[104:105], v[170:171]
	v_cvt_pk_bf16_f32 v112, v110, v111
	v_cvt_pk_bf16_f32 v113, v108, v109
	v_cvt_pk_bf16_f32 v115, v106, v107
	v_lshl_add_u64 v[170:171], v[144:145], 0, s[14:15]
	v_cvt_pk_bf16_f32 v114, v104, v105
	global_store_dwordx4 v[174:175], v[112:115], off
	s_nop 0
	v_lshl_add_u64 v[172:173], v[170:171], 2, s[30:31]
	v_lshl_add_u64 v[170:171], v[170:171], 1, s[34:35]
	s_waitcnt vmcnt(15)
	s_nop 1
	v_mov_b32_e32 v112, v194
	v_mov_b32_e32 v113, v195
	v_mov_b32_e32 v114, v196
	v_mov_b32_e32 v115, v197
	v_mov_b32_e32 v166, v198
	v_mov_b32_e32 v167, v199
	v_mov_b32_e32 v168, v200
	v_mov_b32_e32 v169, v201
	v_pk_add_f32 v[102:103], v[102:103], v[114:115]
	v_pk_add_f32 v[100:101], v[100:101], v[112:113]
	v_pk_add_f32 v[94:95], v[94:95], v[168:169]
	v_pk_add_f32 v[92:93], v[92:93], v[166:167]
	v_cvt_pk_bf16_f32 v112, v100, v101
	v_cvt_pk_bf16_f32 v113, v102, v103
	v_cvt_pk_bf16_f32 v115, v94, v95
	s_nop 0
	v_cvt_pk_bf16_f32 v114, v92, v93
	global_store_dwordx4 v[174:175], v[112:115], off offset:256
	s_nop 0
	s_waitcnt vmcnt(14)
	s_nop 1
	v_mov_b32_e32 v112, v202
	v_mov_b32_e32 v113, v203
	v_mov_b32_e32 v114, v204
	v_mov_b32_e32 v115, v205
	v_mov_b32_e32 v166, v206
	v_mov_b32_e32 v167, v207
	v_mov_b32_e32 v168, v208
	v_mov_b32_e32 v169, v209
	v_pk_add_f32 v[98:99], v[98:99], v[114:115]
	v_pk_add_f32 v[96:97], v[96:97], v[112:113]
	v_pk_add_f32 v[90:91], v[90:91], v[168:169]
	v_pk_add_f32 v[88:89], v[88:89], v[166:167]
	v_cvt_pk_bf16_f32 v112, v96, v97
	v_cvt_pk_bf16_f32 v113, v98, v99
	v_cvt_pk_bf16_f32 v115, v90, v91
	s_nop 0
	v_cvt_pk_bf16_f32 v114, v88, v89
	global_store_dwordx4 v[170:171], v[112:115], off
	s_nop 0
	v_lshl_add_u64 v[172:173], v[144:145], 0, s[16:17]
	v_lshl_add_u64 v[174:175], v[172:173], 2, s[30:31]
	s_waitcnt vmcnt(13)
	s_nop 1
	v_mov_b32_e32 v112, v210
	v_mov_b32_e32 v113, v211
	v_mov_b32_e32 v114, v212
	v_mov_b32_e32 v115, v213
	v_mov_b32_e32 v166, v214
	v_mov_b32_e32 v167, v215
	v_mov_b32_e32 v168, v216
	v_mov_b32_e32 v169, v217
	v_pk_add_f32 v[86:87], v[86:87], v[114:115]
	v_pk_add_f32 v[84:85], v[84:85], v[112:113]
	v_pk_add_f32 v[78:79], v[78:79], v[168:169]
	v_pk_add_f32 v[76:77], v[76:77], v[166:167]
	v_cvt_pk_bf16_f32 v112, v84, v85
	v_cvt_pk_bf16_f32 v113, v86, v87
	v_cvt_pk_bf16_f32 v115, v78, v79
	v_mul_f32_e32 v85, v85, v85
	v_cvt_pk_bf16_f32 v114, v76, v77
	global_store_dwordx4 v[170:171], v[112:115], off offset:256
	s_nop 0
	v_lshl_add_u64 v[170:171], v[172:173], 1, s[34:35]
	v_lshl_add_u64 v[172:173], v[144:145], 0, s[18:19]
	v_fmac_f32_e32 v85, v84, v84
	v_fmac_f32_e32 v85, v86, v86
	v_fmac_f32_e32 v85, v87, v87
	v_fmac_f32_e32 v85, v76, v76
	v_fmac_f32_e32 v85, v77, v77
	v_fmac_f32_e32 v85, v78, v78
	v_fmac_f32_e32 v85, v79, v79
	s_waitcnt vmcnt(12)
	s_nop 1
	v_mov_b32_e32 v112, v218
	v_mov_b32_e32 v113, v219
	v_mov_b32_e32 v114, v220
	v_mov_b32_e32 v115, v221
	v_mov_b32_e32 v166, v222
	v_mov_b32_e32 v167, v223
	v_mov_b32_e32 v168, v224
	v_mov_b32_e32 v169, v225
	v_pk_add_f32 v[82:83], v[82:83], v[114:115]
	v_pk_add_f32 v[80:81], v[80:81], v[112:113]
	v_pk_add_f32 v[74:75], v[74:75], v[168:169]
	v_pk_add_f32 v[72:73], v[72:73], v[166:167]
	v_cvt_pk_bf16_f32 v112, v80, v81
	v_cvt_pk_bf16_f32 v113, v82, v83
	v_cvt_pk_bf16_f32 v115, v74, v75
	v_mul_f32_e32 v86, v81, v81
	v_cvt_pk_bf16_f32 v114, v72, v73
	global_store_dwordx4 v[170:171], v[112:115], off
	s_nop 0
	v_lshl_add_u64 v[174:175], v[172:173], 2, s[30:31]
	v_fmac_f32_e32 v86, v80, v80
	v_fmac_f32_e32 v86, v82, v82
	v_fmac_f32_e32 v86, v83, v83
	v_fmac_f32_e32 v86, v72, v72
	v_fmac_f32_e32 v86, v73, v73
	v_fmac_f32_e32 v86, v74, v74
	v_fmac_f32_e32 v86, v75, v75
	s_waitcnt vmcnt(11)
	s_nop 1
	v_mov_b32_e32 v112, v226
	v_mov_b32_e32 v113, v227
	v_mov_b32_e32 v114, v228
	v_mov_b32_e32 v115, v229
	v_mov_b32_e32 v166, v230
	v_mov_b32_e32 v167, v231
	v_mov_b32_e32 v168, v232
	v_mov_b32_e32 v169, v233
	v_pk_add_f32 v[70:71], v[70:71], v[114:115]
	v_pk_add_f32 v[68:69], v[68:69], v[112:113]
	v_pk_add_f32 v[66:67], v[66:67], v[168:169]
	v_pk_add_f32 v[64:65], v[64:65], v[166:167]
	v_cvt_pk_bf16_f32 v112, v68, v69
	v_cvt_pk_bf16_f32 v113, v70, v71
	v_cvt_pk_bf16_f32 v115, v66, v67
	s_nop 0
	v_cvt_pk_bf16_f32 v114, v64, v65
	global_store_dwordx4 v[170:171], v[112:115], off offset:256
	s_nop 0
	v_lshl_add_u64 v[170:171], v[172:173], 1, s[34:35]
	v_lshl_add_u64 v[172:173], v[144:145], 0, s[20:21]
	s_waitcnt vmcnt(10)
	s_nop 1
	v_mov_b32_e32 v112, v234
	v_mov_b32_e32 v113, v235
	v_mov_b32_e32 v114, v236
	v_mov_b32_e32 v115, v237
	v_mov_b32_e32 v166, v238
	v_mov_b32_e32 v167, v239
	v_mov_b32_e32 v168, v240
	v_mov_b32_e32 v169, v241
	v_pk_add_f32 v[62:63], v[62:63], v[114:115]
	v_pk_add_f32 v[60:61], v[60:61], v[112:113]
	v_pk_add_f32 v[58:59], v[58:59], v[168:169]
	v_pk_add_f32 v[56:57], v[56:57], v[166:167]
	v_cvt_pk_bf16_f32 v112, v60, v61
	v_cvt_pk_bf16_f32 v113, v62, v63
	v_cvt_pk_bf16_f32 v115, v58, v59
	s_nop 0
	v_cvt_pk_bf16_f32 v114, v56, v57
	global_store_dwordx4 v[170:171], v[112:115], off
	s_nop 0
	v_lshl_add_u64 v[174:175], v[172:173], 2, s[30:31]
	s_waitcnt vmcnt(9)
	s_nop 1
	v_mov_b32_e32 v112, v242
	v_mov_b32_e32 v113, v243
	v_mov_b32_e32 v114, v244
	v_mov_b32_e32 v115, v245
	v_mov_b32_e32 v166, v246
	v_mov_b32_e32 v167, v247
	v_mov_b32_e32 v168, v248
	v_mov_b32_e32 v169, v249
	v_pk_add_f32 v[54:55], v[54:55], v[114:115]
	v_pk_add_f32 v[52:53], v[52:53], v[112:113]
	v_pk_add_f32 v[46:47], v[46:47], v[168:169]
	v_pk_add_f32 v[44:45], v[44:45], v[166:167]
	v_cvt_pk_bf16_f32 v112, v52, v53
	v_cvt_pk_bf16_f32 v113, v54, v55
	v_cvt_pk_bf16_f32 v115, v46, v47
	s_nop 0
	v_cvt_pk_bf16_f32 v114, v44, v45
	global_store_dwordx4 v[170:171], v[112:115], off offset:256
	global_load_dwordx4 v[112:115], v[174:175], off
	s_nop 0
	global_load_dwordx4 v[166:169], v[174:175], off offset:16
	v_lshl_add_u64 v[170:171], v[172:173], 1, s[34:35]
	v_lshl_add_u64 v[172:173], v[144:145], 0, s[22:23]
	v_lshl_add_u64 v[144:145], v[144:145], 0, s[24:25]
	s_waitcnt vmcnt(0)
	v_pk_add_f32 v[50:51], v[50:51], v[114:115]
	v_pk_add_f32 v[48:49], v[48:49], v[112:113]
	v_pk_add_f32 v[42:43], v[42:43], v[168:169]
	v_pk_add_f32 v[40:41], v[40:41], v[166:167]
	v_cvt_pk_bf16_f32 v112, v48, v49
	v_cvt_pk_bf16_f32 v113, v50, v51
	v_cvt_pk_bf16_f32 v115, v42, v43
	s_nop 0
	v_cvt_pk_bf16_f32 v114, v40, v41
	global_store_dwordx4 v[170:171], v[112:115], off
	global_load_dwordx4 v[112:115], v[174:175], off offset:512
	s_nop 0
	global_load_dwordx4 v[166:169], v[174:175], off offset:528
	v_lshl_add_u64 v[174:175], v[172:173], 2, s[30:31]
	s_waitcnt vmcnt(0)
	v_pk_add_f32 v[38:39], v[38:39], v[114:115]
	v_pk_add_f32 v[36:37], v[36:37], v[112:113]
	v_pk_add_f32 v[30:31], v[30:31], v[168:169]
	v_pk_add_f32 v[28:29], v[28:29], v[166:167]
	v_cvt_pk_bf16_f32 v112, v36, v37
	v_cvt_pk_bf16_f32 v113, v38, v39
	v_cvt_pk_bf16_f32 v115, v30, v31
	v_mul_f32_e32 v37, v37, v37
	v_cvt_pk_bf16_f32 v114, v28, v29
	global_store_dwordx4 v[170:171], v[112:115], off offset:256
	global_load_dwordx4 v[112:115], v[174:175], off
	s_nop 0
	global_load_dwordx4 v[166:169], v[174:175], off offset:16
	v_lshl_add_u64 v[170:171], v[172:173], 1, s[34:35]
	v_lshl_add_u64 v[172:173], v[144:145], 2, s[30:31]
	v_fmac_f32_e32 v37, v36, v36
	v_fmac_f32_e32 v37, v38, v38
	v_fmac_f32_e32 v37, v39, v39
	v_fmac_f32_e32 v37, v28, v28
	v_fmac_f32_e32 v37, v29, v29
	v_fmac_f32_e32 v37, v30, v30
	v_fmac_f32_e32 v37, v31, v31
	s_waitcnt vmcnt(0)
	v_pk_add_f32 v[34:35], v[34:35], v[114:115]
	v_pk_add_f32 v[32:33], v[32:33], v[112:113]
	v_pk_add_f32 v[26:27], v[26:27], v[168:169]
	v_pk_add_f32 v[24:25], v[24:25], v[166:167]
	v_cvt_pk_bf16_f32 v112, v32, v33
	v_cvt_pk_bf16_f32 v113, v34, v35
	v_cvt_pk_bf16_f32 v115, v26, v27
	v_mul_f32_e32 v29, v33, v33
	v_cvt_pk_bf16_f32 v114, v24, v25
	global_store_dwordx4 v[170:171], v[112:115], off
	global_load_dwordx4 v[112:115], v[174:175], off offset:512
	s_nop 0
	global_load_dwordx4 v[166:169], v[174:175], off offset:528
	v_fmac_f32_e32 v29, v32, v32
	v_fmac_f32_e32 v29, v34, v34
	v_fmac_f32_e32 v29, v35, v35
	v_fmac_f32_e32 v29, v24, v24
	v_fmac_f32_e32 v29, v25, v25
	v_fmac_f32_e32 v29, v26, v26
	v_fmac_f32_e32 v29, v27, v27
	s_waitcnt vmcnt(0)
	v_pk_add_f32 v[174:175], v[22:23], v[114:115]
	v_pk_add_f32 v[176:177], v[20:21], v[112:113]
	v_pk_add_f32 v[168:169], v[18:19], v[168:169]
	v_pk_add_f32 v[166:167], v[16:17], v[166:167]
	v_cvt_pk_bf16_f32 v16, v176, v177
	v_cvt_pk_bf16_f32 v17, v174, v175
	v_cvt_pk_bf16_f32 v19, v168, v169
	v_mul_f32_e32 v24, v177, v177
	v_cvt_pk_bf16_f32 v18, v166, v167
	global_store_dwordx4 v[170:171], v[16:19], off offset:256
	global_load_dwordx4 v[20:23], v[172:173], off
	global_load_dwordx4 v[112:115], v[172:173], off offset:16
	v_mul_f32_e32 v19, v101, v101
	v_fmac_f32_e32 v19, v100, v100
	v_fmac_f32_e32 v19, v102, v102
	v_fmac_f32_e32 v19, v103, v103
	v_fmac_f32_e32 v19, v92, v92
	v_fmac_f32_e32 v19, v93, v93
	v_lshl_add_u64 v[92:93], v[144:145], 1, s[34:35]
	v_fmac_f32_e32 v24, v176, v176
	v_fmac_f32_e32 v24, v174, v174
	v_fmac_f32_e32 v24, v175, v175
	v_fmac_f32_e32 v24, v166, v166
	v_fmac_f32_e32 v24, v167, v167
	v_fmac_f32_e32 v24, v168, v168
	v_fmac_f32_e32 v24, v169, v169
	v_add_f32_e32 v26, v29, v24
	v_mul_f32_e32 v16, v125, v125
	v_mul_f32_e32 v17, v149, v149
	v_mul_f32_e32 v18, v111, v111
	v_fmac_f32_e32 v19, v94, v94
	v_mul_f32_e32 v94, v97, v97
	v_fmac_f32_e32 v16, v124, v124
	v_fmac_f32_e32 v17, v148, v148
	v_fmac_f32_e32 v18, v110, v110
	v_fmac_f32_e32 v94, v96, v96
	v_fmac_f32_e32 v16, v126, v126
	v_fmac_f32_e32 v17, v118, v118
	v_fmac_f32_e32 v18, v108, v108
	v_fmac_f32_e32 v94, v98, v98
	v_fmac_f32_e32 v16, v127, v127
	v_fmac_f32_e32 v17, v119, v119
	v_fmac_f32_e32 v18, v109, v109
	v_fmac_f32_e32 v94, v99, v99
	v_fmac_f32_e32 v16, v120, v120
	v_fmac_f32_e32 v17, v146, v146
	v_fmac_f32_e32 v18, v104, v104
	v_fmac_f32_e32 v94, v88, v88
	v_fmac_f32_e32 v16, v121, v121
	v_fmac_f32_e32 v17, v147, v147
	v_fmac_f32_e32 v18, v105, v105
	v_fmac_f32_e32 v94, v89, v89
	v_fmac_f32_e32 v16, v122, v122
	v_fmac_f32_e32 v17, v116, v116
	v_fmac_f32_e32 v18, v106, v106
	v_fmac_f32_e32 v94, v90, v90
	v_fmac_f32_e32 v16, v123, v123
	v_fmac_f32_e32 v17, v117, v117
	v_fmac_f32_e32 v18, v107, v107
	v_fmac_f32_e32 v19, v95, v95
	v_fmac_f32_e32 v94, v91, v91
	v_add_f32_e32 v16, v16, v17
	v_add_f32_e32 v18, v18, v19
	v_add_f32_e32 v84, v94, v85
	ds_bpermute_b32 v17, v153, v16
	ds_bpermute_b32 v19, v153, v18
	ds_bpermute_b32 v85, v153, v84
	ds_bpermute_b32 v27, v153, v26
	s_waitcnt lgkmcnt(0)
	v_add_f32_e32 v16, v16, v17
	v_add_f32_e32 v18, v18, v19
	ds_bpermute_b32 v17, v154, v16
	ds_bpermute_b32 v19, v154, v18
	s_waitcnt vmcnt(1)
	v_pk_add_f32 v[14:15], v[14:15], v[22:23]
	v_pk_add_f32 v[72:73], v[12:13], v[20:21]
	s_waitcnt vmcnt(0)
	v_pk_add_f32 v[80:81], v[10:11], v[114:115]
	v_pk_add_f32 v[82:83], v[8:9], v[112:113]
	v_cvt_pk_bf16_f32 v8, v72, v73
	v_cvt_pk_bf16_f32 v9, v14, v15
	v_cvt_pk_bf16_f32 v11, v80, v81
	v_mul_f32_e32 v29, v73, v73
	v_cvt_pk_bf16_f32 v10, v82, v83
	global_store_dwordx4 v[92:93], v[8:11], off
	global_load_dwordx4 v[20:23], v[172:173], off offset:528
	global_load_dwordx4 v[76:79], v[172:173], off offset:512
	v_mul_f32_e32 v8, v69, v69
	v_fmac_f32_e32 v8, v68, v68
	v_fmac_f32_e32 v8, v70, v70
	v_fmac_f32_e32 v8, v71, v71
	v_fmac_f32_e32 v8, v64, v64
	v_fmac_f32_e32 v8, v65, v65
	v_fmac_f32_e32 v8, v66, v66
	v_fmac_f32_e32 v8, v67, v67
	v_add_f32_e32 v10, v86, v8
	v_mul_f32_e32 v8, v61, v61
	v_mul_f32_e32 v9, v53, v53
	v_fmac_f32_e32 v8, v60, v60
	v_fmac_f32_e32 v9, v52, v52
	v_fmac_f32_e32 v8, v62, v62
	v_fmac_f32_e32 v9, v54, v54
	v_fmac_f32_e32 v8, v63, v63
	v_fmac_f32_e32 v9, v55, v55
	v_fmac_f32_e32 v8, v56, v56
	v_fmac_f32_e32 v9, v44, v44
	v_fmac_f32_e32 v8, v57, v57
	v_fmac_f32_e32 v9, v45, v45
	v_fmac_f32_e32 v8, v58, v58
	v_fmac_f32_e32 v9, v46, v46
	v_fmac_f32_e32 v8, v59, v59
	v_fmac_f32_e32 v9, v47, v47
	v_add_f32_e32 v12, v8, v9
	ds_bpermute_b32 v13, v153, v12
	v_fmac_f32_e32 v29, v72, v72
	v_fmac_f32_e32 v29, v14, v14
	v_fmac_f32_e32 v29, v15, v15
	v_fmac_f32_e32 v29, v82, v82
	s_waitcnt lgkmcnt(0)
	v_add_f32_e32 v12, v12, v13
	v_mul_f32_e32 v13, v49, v49
	v_fmac_f32_e32 v13, v48, v48
	v_fmac_f32_e32 v13, v50, v50
	v_fmac_f32_e32 v13, v51, v51
	v_fmac_f32_e32 v13, v40, v40
	v_fmac_f32_e32 v13, v41, v41
	v_fmac_f32_e32 v29, v83, v83
	v_fmac_f32_e32 v13, v42, v42
	v_fmac_f32_e32 v29, v80, v80
	v_fmac_f32_e32 v13, v43, v43
	v_fmac_f32_e32 v29, v81, v81
	v_add_f32_e32 v13, v13, v37
	ds_bpermute_b32 v11, v153, v10
	ds_bpermute_b32 v28, v153, v13
	v_add_f32_e32 v8, v84, v85
	ds_bpermute_b32 v9, v154, v8
	s_waitcnt lgkmcnt(2)
	v_add_f32_e32 v10, v10, v11
	ds_bpermute_b32 v11, v154, v10
	s_waitcnt vmcnt(1)
	v_pk_add_f32 v[24:25], v[2:3], v[22:23]
	s_waitcnt vmcnt(0)
	v_pk_add_f32 v[4:5], v[4:5], v[76:77]
	v_pk_add_f32 v[22:23], v[0:1], v[20:21]
	v_mul_f32_e32 v0, v5, v5
	v_pk_add_f32 v[14:15], v[6:7], v[78:79]
	v_fmac_f32_e32 v0, v4, v4
	v_fmac_f32_e32 v0, v14, v14
	v_fmac_f32_e32 v0, v15, v15
	v_fmac_f32_e32 v0, v22, v22
	v_fmac_f32_e32 v0, v23, v23
	v_fmac_f32_e32 v0, v24, v24
	v_fmac_f32_e32 v0, v25, v25
	v_cvt_pk_bf16_f32 v20, v4, v5
	v_add_f32_e32 v5, v29, v0
	ds_bpermute_b32 v6, v153, v5
	s_waitcnt lgkmcnt(3)
	v_add_f32_e32 v1, v13, v28
	v_add_f32_e32 v3, v26, v27
	ds_bpermute_b32 v0, v154, v12
	ds_bpermute_b32 v2, v154, v1
	s_waitcnt lgkmcnt(2)
	v_add_f32_e32 v5, v5, v6
	ds_bpermute_b32 v4, v154, v3
	ds_bpermute_b32 v6, v154, v5
	v_cvt_pk_bf16_f32 v21, v14, v15
	v_cvt_pk_bf16_f32 v22, v22, v23
	v_cvt_pk_bf16_f32 v23, v24, v25
	global_store_dwordx4 v[92:93], v[20:23], off offset:256
	s_and_saveexec_b64 s[30:31], s[0:1]
	s_cbranch_execz .LBB0_335
	s_waitcnt lgkmcnt(0)
	v_add_f32_e32 v5, v5, v6
	v_add_f32_e32 v3, v3, v4
	v_add_f32_e32 v1, v1, v2
	v_add_f32_e32 v2, v10, v11
	v_add_f32_e32 v4, v8, v9
	v_add_f32_e32 v6, v18, v19
	v_add_f32_e32 v7, v16, v17
	v_add_u32_e32 v8, s53, v155
	v_add_f32_e32 v0, v12, v0
	ds_write2st64_b32 v8, v7, v6 offset1:1
	ds_write2st64_b32 v8, v4, v2 offset0:2 offset1:3
	v_add_u32_e32 v2, s53, v159
	ds_write2st64_b32 v2, v0, v1 offset1:1
	ds_write2st64_b32 v2, v3, v5 offset0:2 offset1:3
